# attention main loop: K/V DMA issue moved into PV MFMA gaps and first QK MFMA of the odd step issued at loop top; plus global_* ops and deferred SSQ atomics
# speedup vs baseline: 1.0118x; 1.0118x over previous
.LBB0_1062:
	s_mov_b32 s34, s18
	s_mov_b32 s1, s12
	v_mfma_f32_32x32x16_bf16 v[130:145], v[206:209], v[174:177], 0
	v_lshl_add_u32 v218, s4, 1, v240
	ds_read_b64_tr_b16 v[68:69], v218 offset:24576
	ds_read_b64_tr_b16 v[70:71], v218 offset:25088
	v_add_f32_e32 v67, v98, v99
	v_add_f32_e32 v67, v100, v67
	v_add_f32_e32 v67, v101, v67
	v_add_f32_e32 v67, v102, v67
	v_add_f32_e32 v67, v103, v67
	v_cvt_pk_bf16_f32 v162, v98, v99
	v_cvt_pk_bf16_f32 v163, v100, v101
	s_waitcnt lgkmcnt(9)
	ds_read_b64_tr_b16 v[72:73], v218 offset:28672
	ds_read_b64_tr_b16 v[74:75], v218 offset:29184
	v_add_f32_e32 v67, v104, v67
	v_add_f32_e32 v67, v105, v67
	v_add_f32_e32 v67, v106, v67
	v_add_f32_e32 v67, v107, v67
	v_cvt_pk_bf16_f32 v164, v102, v103
	v_cvt_pk_bf16_f32 v165, v104, v105
	s_waitcnt lgkmcnt(10)
	v_mfma_f32_32x32x16_bf16 v[114:129], v[202:205], v[174:177], 0
	ds_read_b64_tr_b16 v[76:77], v218 offset:25600
	ds_read_b64_tr_b16 v[78:79], v218 offset:26112
	v_add_f32_e32 v67, v108, v67
	v_add_f32_e32 v67, v109, v67
	v_add_f32_e32 v67, v110, v67
	v_add_f32_e32 v67, v111, v67
	v_cvt_pk_bf16_f32 v158, v106, v107
	v_cvt_pk_bf16_f32 v159, v108, v109
	s_waitcnt lgkmcnt(11)
	v_mfma_f32_32x32x16_bf16 v[130:145], v[198:201], v[170:173], v[130:145]
	ds_read_b64_tr_b16 v[98:99], v218 offset:29696
	ds_read_b64_tr_b16 v[100:101], v218 offset:30208
	v_add_f32_e32 v67, v112, v67
	v_add_f32_e32 v67, v113, v67
	v_add_f32_e32 v67, v82, v67
	v_add_f32_e32 v67, v83, v67
	v_cvt_pk_bf16_f32 v160, v110, v111
	v_cvt_pk_bf16_f32 v161, v112, v113
	s_waitcnt lgkmcnt(12)
	v_mfma_f32_32x32x16_bf16 v[114:129], v[194:197], v[170:173], v[114:129]
	ds_read_b64_tr_b16 v[102:103], v218 offset:26624
	ds_read_b64_tr_b16 v[104:105], v218 offset:27136
	v_add_f32_e32 v67, v84, v67
	v_add_f32_e32 v67, v85, v67
	v_add_f32_e32 v67, v86, v67
	v_add_f32_e32 v67, v87, v67
	v_cvt_pk_bf16_f32 v150, v82, v83
	v_cvt_pk_bf16_f32 v151, v84, v85
	s_waitcnt lgkmcnt(13)
	v_mfma_f32_32x32x16_bf16 v[130:145], v[190:193], v[166:169], v[130:145]
	ds_read_b64_tr_b16 v[106:107], v218 offset:30720
	ds_read_b64_tr_b16 v[108:109], v218 offset:31232
	v_add_f32_e32 v67, v88, v67
	v_add_f32_e32 v67, v89, v67
	v_add_f32_e32 v67, v90, v67
	v_add_f32_e32 v67, v91, v67
	v_cvt_pk_bf16_f32 v152, v86, v87
	v_cvt_pk_bf16_f32 v153, v88, v89
	s_waitcnt lgkmcnt(14)
	v_mfma_f32_32x32x16_bf16 v[114:129], v[186:189], v[166:169], v[114:129]
	ds_read_b64_tr_b16 v[110:111], v218 offset:27648
	ds_read_b64_tr_b16 v[112:113], v218 offset:28160
	v_add_f32_e32 v67, v92, v67
	v_add_f32_e32 v67, v93, v67
	v_add_f32_e32 v67, v94, v67
	v_add_f32_e32 v67, v95, v67
	v_cvt_pk_bf16_f32 v146, v90, v91
	v_cvt_pk_bf16_f32 v147, v92, v93
	s_waitcnt lgkmcnt(14)
	v_mfma_f32_32x32x16_bf16 v[130:145], v[182:185], v[154:157], v[130:145]
	ds_read_b64_tr_b16 v[90:91], v218 offset:31744
	ds_read_b64_tr_b16 v[92:93], v218 offset:32256
	v_add_f32_e32 v67, v96, v67
	v_add_f32_e32 v67, v97, v67
	v_add_f32_e32 v67, 0, v67
	v_cvt_pk_bf16_f32 v148, v94, v95
	v_cvt_pk_bf16_f32 v149, v96, v97
	v_mfma_f32_32x32x16_bf16 v[114:129], v[178:181], v[154:157], v[114:129]
	v_add_f32_e32 v198, v66, v67
	s_waitcnt lgkmcnt(14)
	v_mfma_f32_32x32x16_bf16 v[34:49], v[162:165], v[68:71], v[34:49]
	v_exp_f32_e32 v130, v130
	v_exp_f32_e32 v131, v131
	ds_read_b64_tr_b16 v[94:95], v218 offset:32768
	ds_read_b64_tr_b16 v[96:97], v218 offset:33280
	s_waitcnt lgkmcnt(14)
	v_mfma_f32_32x32x16_bf16 v[50:65], v[162:165], v[72:75], v[50:65]
	v_exp_f32_e32 v132, v132
	v_exp_f32_e32 v133, v133
	ds_read_b64_tr_b16 v[190:191], v218 offset:36864
	ds_read_b64_tr_b16 v[192:193], v218 offset:37376
	v_add_u32_e32 v66, s34, v238
	ds_read_b128 v[86:89], v66
	ds_read_b128 v[82:85], v66 offset:512
	s_waitcnt lgkmcnt(14)
	v_mfma_f32_32x32x16_bf16 v[34:49], v[158:161], v[76:79], v[34:49]
	v_exp_f32_e32 v134, v134
	v_exp_f32_e32 v135, v135
	ds_read_b64_tr_b16 v[194:195], v218 offset:33792
	ds_read_b64_tr_b16 v[196:197], v218 offset:34304
	ds_read_b128 v[182:185], v66 offset:2048
	ds_read_b128 v[78:81], v66 offset:2560
	v_mfma_f32_32x32x16_bf16 v[50:65], v[158:161], v[98:101], v[50:65]
	v_exp_f32_e32 v136, v136
	v_exp_f32_e32 v137, v137
	ds_read_b64_tr_b16 v[98:99], v218 offset:37888
	ds_read_b64_tr_b16 v[100:101], v218 offset:38400
	ds_read_b128 v[178:181], v66 offset:4096
	ds_read_b128 v[70:73], v66 offset:4608
	s_waitcnt lgkmcnt(14)
	v_mfma_f32_32x32x16_bf16 v[34:49], v[150:153], v[102:105], v[34:49]
	v_exp_f32_e32 v138, v138
	v_exp_f32_e32 v139, v139
	ds_read_b64_tr_b16 v[102:103], v218 offset:34816
	ds_read_b64_tr_b16 v[104:105], v218 offset:35328
	ds_read_b128 v[74:77], v66 offset:6144
	ds_read_b128 v[66:69], v66 offset:6656
	v_mfma_f32_32x32x16_bf16 v[50:65], v[150:153], v[106:109], v[50:65]
	v_exp_f32_e32 v140, v140
	v_exp_f32_e32 v141, v141
	ds_read_b64_tr_b16 v[106:107], v218 offset:38912
	ds_read_b64_tr_b16 v[108:109], v218 offset:39424
	v_mfma_f32_32x32x16_bf16 v[34:49], v[146:149], v[110:113], v[34:49]
	v_exp_f32_e32 v142, v142
	v_exp_f32_e32 v143, v143
	ds_read_b64_tr_b16 v[110:111], v218 offset:35840
	ds_read_b64_tr_b16 v[112:113], v218 offset:36352
	v_mfma_f32_32x32x16_bf16 v[50:65], v[146:149], v[90:93], v[50:65]
	v_exp_f32_e32 v144, v144
	v_exp_f32_e32 v145, v145
	ds_read_b64_tr_b16 v[90:91], v218 offset:39936
	ds_read_b64_tr_b16 v[92:93], v218 offset:40448
	s_waitcnt lgkmcnt(14)
	v_mfma_f32_32x32x16_bf16 v[2:17], v[162:165], v[94:97], v[2:17]
	v_exp_f32_e32 v114, v114
	v_exp_f32_e32 v115, v115
	v_lshl_add_u64 v[250:251], s[8:9], 0, v[216:217]
	s_add_i32 s32, s12, s96
	v_mfma_f32_32x32x16_bf16 v[18:33], v[162:165], v[190:193], v[18:33]
	v_exp_f32_e32 v116, v116
	v_exp_f32_e32 v117, v117
	v_lshl_add_u64 v[244:245], v[250:251], 0, s[22:23]
	s_mov_b32 m0, s32
	v_mfma_f32_32x32x16_bf16 v[2:17], v[158:161], v[194:197], v[2:17]
	v_exp_f32_e32 v118, v118
	v_exp_f32_e32 v119, v119
	global_load_lds_dwordx4 v[244:245], off
	v_lshl_add_u64 v[252:253], s[8:9], 0, v[214:215]
	s_lshl_b32 s32, s18, 1
	s_add_i32 s32, s32, s79
	s_waitcnt lgkmcnt(12)
	v_mfma_f32_32x32x16_bf16 v[18:33], v[158:161], v[98:101], v[18:33]
	v_exp_f32_e32 v120, v120
	v_exp_f32_e32 v121, v121
	v_lshl_add_u64 v[246:247], v[252:253], 0, s[24:25]
	s_mov_b32 m0, s32
	s_waitcnt lgkmcnt(8)
	v_mfma_f32_32x32x16_bf16 v[2:17], v[150:153], v[102:105], v[2:17]
	v_exp_f32_e32 v122, v122
	v_exp_f32_e32 v123, v123
	global_load_lds_dwordx4 v[246:247], off
	v_lshl_add_u64 v[248:249], v[252:253], 0, s[26:27]
	s_addk_i32 s32, 0x2000
	s_waitcnt lgkmcnt(4)
	v_mfma_f32_32x32x16_bf16 v[18:33], v[150:153], v[106:109], v[18:33]
	v_exp_f32_e32 v124, v124
	v_exp_f32_e32 v125, v125
	s_mov_b32 m0, s32
	s_waitcnt lgkmcnt(2)
	v_mfma_f32_32x32x16_bf16 v[2:17], v[146:149], v[110:113], v[2:17]
	v_exp_f32_e32 v126, v126
	v_exp_f32_e32 v127, v127
	global_load_lds_dwordx4 v[248:249], off
	s_waitcnt lgkmcnt(0)
	v_mfma_f32_32x32x16_bf16 v[18:33], v[146:149], v[90:93], v[18:33]
	v_exp_f32_e32 v128, v128
	v_exp_f32_e32 v129, v129
	s_waitcnt vmcnt(3) lgkmcnt(0)
	s_barrier
	s_add_i32 s4, s18, 0x2000
	s_cmpk_lg_i32 s18, 0x4000
	s_cselect_b32 s12, s4, 0
	v_lshl_add_u32 v218, s1, 1, v240
	ds_read_b64_tr_b16 v[190:191], v218 offset:24576
	ds_read_b64_tr_b16 v[192:193], v218 offset:25088
	v_mfma_f32_32x32x16_bf16 v[98:113], v[86:89], v[174:177], 0
	v_add_f32_e32 v90, v130, v131
	v_add_f32_e32 v90, v132, v90
	v_add_f32_e32 v90, v133, v90
	v_add_f32_e32 v90, v134, v90
	v_add_f32_e32 v90, v135, v90
	v_cvt_pk_bf16_f32 v162, v130, v131
	v_cvt_pk_bf16_f32 v163, v132, v133
	ds_read_b64_tr_b16 v[130:131], v218 offset:28672
	ds_read_b64_tr_b16 v[132:133], v218 offset:29184
	v_add_f32_e32 v86, v136, v90
	v_add_f32_e32 v86, v137, v86
	v_add_f32_e32 v86, v138, v86
	v_add_f32_e32 v146, v139, v86
	v_mfma_f32_32x32x16_bf16 v[82:97], v[82:85], v[174:177], 0
	v_cvt_pk_bf16_f32 v164, v134, v135
	v_cvt_pk_bf16_f32 v165, v136, v137
	ds_read_b64_tr_b16 v[134:135], v218 offset:25600
	ds_read_b64_tr_b16 v[136:137], v218 offset:26112
	v_mfma_f32_32x32x16_bf16 v[98:113], v[182:185], v[170:173], v[98:113]
	v_add_f32_e32 v146, v140, v146
	v_add_f32_e32 v146, v141, v146
	v_add_f32_e32 v146, v142, v146
	v_add_f32_e32 v146, v143, v146
	v_cvt_pk_bf16_f32 v158, v138, v139
	v_cvt_pk_bf16_f32 v159, v140, v141
	ds_read_b64_tr_b16 v[138:139], v218 offset:29696
	ds_read_b64_tr_b16 v[140:141], v218 offset:30208
	v_mfma_f32_32x32x16_bf16 v[82:97], v[78:81], v[170:173], v[82:97]
	v_add_f32_e32 v146, v144, v146
	v_add_f32_e32 v146, v145, v146
	v_add_f32_e32 v146, v114, v146
	v_add_f32_e32 v146, v115, v146
	v_cvt_pk_bf16_f32 v160, v142, v143
	v_cvt_pk_bf16_f32 v161, v144, v145
	ds_read_b64_tr_b16 v[78:79], v218 offset:26624
	ds_read_b64_tr_b16 v[80:81], v218 offset:27136
	v_mfma_f32_32x32x16_bf16 v[98:113], v[178:181], v[166:169], v[98:113]
	v_add_f32_e32 v142, v116, v146
	v_add_f32_e32 v142, v117, v142
	v_add_f32_e32 v142, v118, v142
	v_add_f32_e32 v142, v119, v142
	v_cvt_pk_bf16_f32 v150, v114, v115
	v_cvt_pk_bf16_f32 v151, v116, v117
	ds_read_b64_tr_b16 v[114:115], v218 offset:30720
	ds_read_b64_tr_b16 v[116:117], v218 offset:31232
	v_mfma_f32_32x32x16_bf16 v[82:97], v[70:73], v[166:169], v[82:97]
	v_add_f32_e32 v142, v120, v142
	v_add_f32_e32 v142, v121, v142
	v_add_f32_e32 v142, v122, v142
	v_add_f32_e32 v142, v123, v142
	v_cvt_pk_bf16_f32 v152, v118, v119
	v_cvt_pk_bf16_f32 v153, v120, v121
	ds_read_b64_tr_b16 v[70:71], v218 offset:27648
	ds_read_b64_tr_b16 v[72:73], v218 offset:28160
	v_mfma_f32_32x32x16_bf16 v[98:113], v[74:77], v[154:157], v[98:113]
	v_add_f32_e32 v118, v124, v142
	v_add_f32_e32 v118, v125, v118
	v_add_f32_e32 v118, v126, v118
	v_add_f32_e32 v118, v127, v118
	v_cvt_pk_bf16_f32 v146, v122, v123
	v_cvt_pk_bf16_f32 v147, v124, v125
	ds_read_b64_tr_b16 v[74:75], v218 offset:31744
	ds_read_b64_tr_b16 v[76:77], v218 offset:32256
	v_mfma_f32_32x32x16_bf16 v[82:97], v[66:69], v[154:157], v[82:97]
	v_add_f32_e32 v118, v128, v118
	v_add_f32_e32 v118, v129, v118
	v_add_f32_e32 v118, 0, v118
	v_cvt_pk_bf16_f32 v148, v126, v127
	v_cvt_pk_bf16_f32 v149, v128, v129
	v_add_f32_e32 v66, v198, v118
	s_add_i32 s10, s10, 2
	s_waitcnt lgkmcnt(14)
	v_mfma_f32_32x32x16_bf16 v[34:49], v[162:165], v[190:193], v[34:49]
	v_exp_f32_e32 v98, v98
	v_exp_f32_e32 v99, v99
	ds_read_b64_tr_b16 v[118:119], v218 offset:32768
	ds_read_b64_tr_b16 v[120:121], v218 offset:33280
	s_waitcnt lgkmcnt(14)
	v_mfma_f32_32x32x16_bf16 v[50:65], v[162:165], v[130:133], v[50:65]
	v_exp_f32_e32 v100, v100
	v_exp_f32_e32 v101, v101
	ds_read_b64_tr_b16 v[122:123], v218 offset:36864
	ds_read_b64_tr_b16 v[124:125], v218 offset:37376
	v_add_u32_e32 v67, s12, v238
	ds_read_b128 v[206:209], v67
	ds_read_b128 v[202:205], v67 offset:512
	s_waitcnt lgkmcnt(14)
	v_mfma_f32_32x32x16_bf16 v[34:49], v[158:161], v[134:137], v[34:49]
	v_exp_f32_e32 v102, v102
	v_exp_f32_e32 v103, v103
	ds_read_b64_tr_b16 v[126:127], v218 offset:33792
	ds_read_b64_tr_b16 v[128:129], v218 offset:34304
	ds_read_b128 v[198:201], v67 offset:2048
	ds_read_b128 v[194:197], v67 offset:2560
	v_mfma_f32_32x32x16_bf16 v[50:65], v[158:161], v[138:141], v[50:65]
	v_exp_f32_e32 v104, v104
	v_exp_f32_e32 v105, v105
	ds_read_b64_tr_b16 v[130:131], v218 offset:37888
	ds_read_b64_tr_b16 v[132:133], v218 offset:38400
	ds_read_b128 v[190:193], v67 offset:4096
	ds_read_b128 v[186:189], v67 offset:4608
	s_waitcnt lgkmcnt(14)
	v_mfma_f32_32x32x16_bf16 v[34:49], v[150:153], v[78:81], v[34:49]
	v_exp_f32_e32 v106, v106
	v_exp_f32_e32 v107, v107
	ds_read_b64_tr_b16 v[78:79], v218 offset:34816
	ds_read_b64_tr_b16 v[80:81], v218 offset:35328
	ds_read_b128 v[182:185], v67 offset:6144
	ds_read_b128 v[178:181], v67 offset:6656
	v_mfma_f32_32x32x16_bf16 v[50:65], v[150:153], v[114:117], v[50:65]
	v_exp_f32_e32 v108, v108
	v_exp_f32_e32 v109, v109
	ds_read_b64_tr_b16 v[114:115], v218 offset:38912
	ds_read_b64_tr_b16 v[116:117], v218 offset:39424
	v_mfma_f32_32x32x16_bf16 v[34:49], v[146:149], v[70:73], v[34:49]
	v_exp_f32_e32 v110, v110
	v_exp_f32_e32 v111, v111
	ds_read_b64_tr_b16 v[68:69], v218 offset:35840
	ds_read_b64_tr_b16 v[70:71], v218 offset:36352
	v_mfma_f32_32x32x16_bf16 v[50:65], v[146:149], v[74:77], v[50:65]
	v_exp_f32_e32 v112, v112
	v_exp_f32_e32 v113, v113
	ds_read_b64_tr_b16 v[72:73], v218 offset:39936
	ds_read_b64_tr_b16 v[74:75], v218 offset:40448
	s_waitcnt lgkmcnt(14)
	v_mfma_f32_32x32x16_bf16 v[2:17], v[162:165], v[118:121], v[2:17]
	v_exp_f32_e32 v82, v82
	v_exp_f32_e32 v83, v83
	s_add_i32 s32, s18, s96
	v_lshl_add_u64 v[244:245], v[250:251], 0, s[28:29]
	v_mfma_f32_32x32x16_bf16 v[18:33], v[162:165], v[122:125], v[18:33]
	v_exp_f32_e32 v84, v84
	v_exp_f32_e32 v85, v85
	s_mov_b32 m0, s32
	v_mfma_f32_32x32x16_bf16 v[2:17], v[158:161], v[126:129], v[2:17]
	v_exp_f32_e32 v86, v86
	v_exp_f32_e32 v87, v87
	global_load_lds_dwordx4 v[244:245], off
	s_lshl_b32 s32, s12, 1
	v_lshl_add_u64 v[246:247], v[252:253], 0, s[38:39]
	s_add_i32 s32, s32, s79
	s_waitcnt lgkmcnt(12)
	v_mfma_f32_32x32x16_bf16 v[18:33], v[158:161], v[130:133], v[18:33]
	v_exp_f32_e32 v88, v88
	v_exp_f32_e32 v89, v89
	s_mov_b32 m0, s32
	s_waitcnt lgkmcnt(8)
	v_mfma_f32_32x32x16_bf16 v[2:17], v[150:153], v[78:81], v[2:17]
	v_exp_f32_e32 v90, v90
	v_exp_f32_e32 v91, v91
	global_load_lds_dwordx4 v[246:247], off
	v_lshl_add_u64 v[248:249], v[252:253], 0, s[40:41]
	s_addk_i32 s32, 0x2000
	s_waitcnt lgkmcnt(4)
	v_mfma_f32_32x32x16_bf16 v[18:33], v[150:153], v[114:117], v[18:33]
	v_exp_f32_e32 v92, v92
	v_exp_f32_e32 v93, v93
	s_mov_b32 m0, s32
	s_waitcnt lgkmcnt(2)
	v_mfma_f32_32x32x16_bf16 v[2:17], v[146:149], v[68:71], v[2:17]
	v_exp_f32_e32 v94, v94
	v_exp_f32_e32 v95, v95
	global_load_lds_dwordx4 v[248:249], off
	s_waitcnt lgkmcnt(0)
	v_mfma_f32_32x32x16_bf16 v[18:33], v[146:149], v[72:75], v[18:33]
	v_exp_f32_e32 v96, v96
	v_exp_f32_e32 v97, v97
	s_waitcnt vmcnt(3) lgkmcnt(0)
	s_barrier
; #define WAIT_BAR(N) asm volatile("s_waitcnt vmcnt(" #N ") lgkmcnt(0)\n\ts_barrier":::"memory")
;   #define RESC() do{ if constexpr(!FIXED) if(resc){ asm volatile("s_waitcnt lgkmcnt(0)":::"memory"); \
;       _Pragma("unroll") for(int d_=0;d_<4;++d_) _Pragma("unroll") for(int r=0;r<16;++r)o[d_][r]*=wsf[crow(r,hi)]; } }while(0)
;   #define ROT() do{sl_prev=sl_cur;sl_cur=sl_next;sl_next=(sl_next==(NSLOT-1)*SLOTB)?0:sl_next+SLOTB;}while(0)
; template<int THRL,bool FIXED> __device__ __forceinline__ void attn_unit(int qb,const bf16*Q,const bf16*__restrict__ Kh,const bf16*__restrict__ Vh,bf16*O,const int*__restrict__ cid,char*shm,const int wid){
;     ...
;   for(;t+5<NT;t+=2){
;     STEP(pB0,pB1,pA0,pA1,t,true,true,true);     WAIT_BAR(3); RESC(); ROT();
;     STEP(pA0,pA1,pB0,pB1,t+1,true,true,true);   WAIT_BAR(3); RESC(); ROT();
;   }
	s_add_i32 s1, s12, 0x2000
	s_cmpk_lg_i32 s12, 0x4000
	s_cselect_b32 s18, s1, 0
	v_lshl_add_u64 v[214:215], v[214:215], 0, s[16:17]
	v_lshl_add_u64 v[216:217], v[216:217], 0, s[16:17]
	s_cmp_ge_i32 s10, s0
	s_mov_b32 s4, s34
	s_cbranch_scc0 .LBB0_1062
	s_add_i32 s0, s10, 1
	s_cmp_lt_i32 s0, s13
	v_lshlrev_b32_e32 v67, 4, v234
	s_cbranch_scc1 .LBB0_1069
